# adaLN RMSNorm phase software-pipelined: each wave requests its next latent row (f32 row in layer 0, bf16 copy in layer 1) before the current row's reduction and stores; one row was loaded, waited for
# speedup vs baseline: 1.0028x; 1.0028x over previous
.LBB0_179:
	v_lshrrev_b32_e32 v96, 6, v138
	v_and_b32_e32 v98, 63, v138
	v_readfirstlane_b32 s8, v96
	v_lshlrev_b32_e32 v104, 4, v98
	v_lshlrev_b32_e32 v105, 3, v98
	v_xor_b32_e32 v106, 32, v98
	v_lshlrev_b32_e32 v106, 2, v106
	v_xor_b32_e32 v107, 16, v98
	v_lshlrev_b32_e32 v107, 2, v107
	v_xor_b32_e32 v108, 8, v98
	v_lshlrev_b32_e32 v108, 2, v108
	v_xor_b32_e32 v110, 4, v98
	v_lshlrev_b32_e32 v110, 2, v110
	v_xor_b32_e32 v111, 2, v98
	v_lshlrev_b32_e32 v111, 2, v111
	v_xor_b32_e32 v112, 1, v98
	v_lshlrev_b32_e32 v112, 2, v112
	v_readlane_b32 s2, v207, 52
	v_readlane_b32 s3, v207, 53
	s_nop 0
	s_load_dword s18, s[2:3], 0x0
	s_lshl_b32 s9, s96, 2
	s_add_u32 s9, s9, s8
	s_waitcnt lgkmcnt(0)
	s_lshl_b32 s18, s18, 2
	s_lshl_b32 s2, s50, 12
	v_readlane_b32 s76, v207, 16
	v_readlane_b32 s77, v207, 17
	s_add_u32 s76, s76, s2
	s_addc_u32 s77, s77, 0
	s_mul_i32 s2, s50, 0x9000
	s_add_u32 s2, s2, 0x4000
	s_add_u32 s78, s94, s2
	s_addc_u32 s79, s95, 0
	s_add_u32 s80, s94, 0x1100000
	s_addc_u32 s81, s95, 0
	v_readlane_b32 s82, v207, 4
	v_readlane_b32 s83, v207, 5
	s_add_u32 s84, s94, 0xa700000
	s_addc_u32 s85, s95, 0
	v_readlane_b32 s86, v207, 8
	v_readlane_b32 s87, v207, 9
	s_add_u32 s88, s94, 0xa500000
	s_addc_u32 s89, s95, 0
	s_add_u32 s90, s94, 0xc700000
	s_addc_u32 s91, s95, 0
	global_load_dwordx4 v[16:19], v104, s[76:77]
	global_load_dwordx4 v[20:23], v104, s[76:77] offset:1024
	global_load_dwordx4 v[24:27], v104, s[76:77] offset:2048
	global_load_dwordx4 v[28:31], v104, s[76:77] offset:3072
	s_mov_b32 s16, -1
	s_mov_b32 s76, -1

.Lnm_have_mv:
	s_cmpk_lt_u32 s9, 0x4000
	s_cbranch_scc0 .Lnm_ctxrow
	s_cmp_eq_u32 s50, 0
	s_cbranch_scc0 .Lnm_bf16row
	s_cmp_eq_u32 s76, s9
	s_cbranch_scc1 .Lnm_f32_pf
	s_lshl_b32 s2, s9, 12
	s_add_u32 s12, s82, s2
	s_addc_u32 s13, s83, 0
	global_load_dwordx4 v[208:211], v104, s[12:13] nt
	global_load_dwordx4 v[212:215], v104, s[12:13] offset:1024 nt
	global_load_dwordx4 v[216:219], v104, s[12:13] offset:2048 nt
	global_load_dwordx4 v[220:223], v104, s[12:13] offset:3072 nt
	s_waitcnt vmcnt(0)
	s_branch .Lnm_f32_copy
.Lnm_f32_pf:
	s_waitcnt vmcnt(4)
.Lnm_f32_copy:
	v_mov_b32_e32 v0, v208
	v_mov_b32_e32 v1, v209
	v_mov_b32_e32 v2, v210
	v_mov_b32_e32 v3, v211
	v_mov_b32_e32 v4, v212
	v_mov_b32_e32 v5, v213
	v_mov_b32_e32 v6, v214
	v_mov_b32_e32 v7, v215
	v_mov_b32_e32 v8, v216
	v_mov_b32_e32 v9, v217
	v_mov_b32_e32 v10, v218
	v_mov_b32_e32 v11, v219
	v_mov_b32_e32 v12, v220
	v_mov_b32_e32 v13, v221
	v_mov_b32_e32 v14, v222
	v_mov_b32_e32 v15, v223
	s_add_u32 s76, s9, s18
	s_cmpk_lt_u32 s76, 0x4000
	s_cbranch_scc0 .Lnm_math
	s_lshl_b32 s2, s76, 12
	s_add_u32 s12, s82, s2
	s_addc_u32 s13, s83, 0
	global_load_dwordx4 v[208:211], v104, s[12:13] nt
	global_load_dwordx4 v[212:215], v104, s[12:13] offset:1024 nt
	global_load_dwordx4 v[216:219], v104, s[12:13] offset:2048 nt
	global_load_dwordx4 v[220:223], v104, s[12:13] offset:3072 nt
	s_branch .Lnm_math
.Lnm_bf16row:
	s_cmp_eq_u32 s76, s9
	s_cbranch_scc1 .Lnm_b16_pf
	s_lshl_b32 s2, s9, 11
	s_add_u32 s12, s84, s2
	s_addc_u32 s13, s85, 0
	global_load_dwordx2 v[224:225], v105, s[12:13]
	global_load_dwordx2 v[226:227], v105, s[12:13] offset:512
	global_load_dwordx2 v[228:229], v105, s[12:13] offset:1024
	global_load_dwordx2 v[230:231], v105, s[12:13] offset:1536
	s_waitcnt vmcnt(0)
	s_branch .Lnm_b16_unpack

.Lnm_b16_unpack:
	v_lshlrev_b32_e32 v0, 16, v224
	v_and_b32_e32 v1, 0xffff0000, v224
	v_lshlrev_b32_e32 v2, 16, v225
	v_and_b32_e32 v3, 0xffff0000, v225
	v_lshlrev_b32_e32 v4, 16, v226
	v_and_b32_e32 v5, 0xffff0000, v226
	v_lshlrev_b32_e32 v6, 16, v227
	v_and_b32_e32 v7, 0xffff0000, v227
	v_lshlrev_b32_e32 v8, 16, v228
	v_and_b32_e32 v9, 0xffff0000, v228
	v_lshlrev_b32_e32 v10, 16, v229
	v_and_b32_e32 v11, 0xffff0000, v229
	v_lshlrev_b32_e32 v12, 16, v230
	v_and_b32_e32 v13, 0xffff0000, v230
	v_lshlrev_b32_e32 v14, 16, v231
	v_and_b32_e32 v15, 0xffff0000, v231
	s_add_u32 s76, s9, s18
	s_cmpk_lt_u32 s76, 0x4000
	s_cbranch_scc0 .Lnm_math
	s_lshl_b32 s2, s76, 11
	s_add_u32 s12, s84, s2
	s_addc_u32 s13, s85, 0
	global_load_dwordx2 v[224:225], v105, s[12:13]
	global_load_dwordx2 v[226:227], v105, s[12:13] offset:512
	global_load_dwordx2 v[228:229], v105, s[12:13] offset:1024
	global_load_dwordx2 v[230:231], v105, s[12:13] offset:1536
	s_branch .Lnm_math
